# P6->P7 grid barrier replaced by a grid-wide arrival counter that only the 16 workgroups owning sample rows in P7 wait on
# baseline (speedup 1.0000x reference)
; __device__ __forceinline__ unsigned xb_ld(unsigned* p) { return __hip_atomic_load(p, __ATOMIC_RELAXED, __HIP_MEMORY_SCOPE_AGENT); }
; __device__ __forceinline__ unsigned xb_add(unsigned* p, unsigned v) { return __hip_atomic_fetch_add(p, v, __ATOMIC_RELAXED, __HIP_MEMORY_SCOPE_AGENT); }
; __device__ __forceinline__ void xcd_barrier(const XB& b) {
;     __syncthreads();
;     if (threadIdx.x == 0) {
;         unsigned* bar = b.bar;
;         __builtin_amdgcn_fence(__ATOMIC_RELEASE, "agent");
;         asm volatile("s_waitcnt vmcnt(0)" ::: "memory");
;         const unsigned old = xb_add(&bar[XB_XSUB(b.x)], 1u);
;         const unsigned gen = old / b.nloc;
;         if (old + 1u == (gen + 1u) * b.nloc) {
;             const unsigned og = xb_add(&bar[XB_TOP], 1u);
;             const unsigned target = (og / b.nx + 1u) * b.nx;
;             if (og + 1u != target) while (xb_ld(&bar[XB_TOP]) < target) __builtin_amdgcn_s_sleep(1);
;             xb_add(&bar[XB_XGEN(b.x)], 1u);
;         } else {
;             while (xb_ld(&bar[XB_XGEN(b.x)]) == gen) __builtin_amdgcn_s_sleep(1);
;         }
;         __builtin_amdgcn_fence(__ATOMIC_ACQUIRE, "agent");
;         asm volatile("s_waitcnt vmcnt(0)" ::: "memory");
;     }
;     __syncthreads();
; __device__ __forceinline__ void p7_final(const Params& p, bool prompt_done) {
;     ...
;     for (int s = blockIdx.x * 8 + wave; s < MS; s += stride) {
;         float* xr = p.out + O_YS + (size_t)s * D;
;         const float rstd = rsqrtf(SS2[MP + s] * (1.f / D) + EPS);
; #pragma unroll
;         for (int j = 0; j < 4; ++j) { const f32x4 v = *(const f32x4*)(xr + lane * 4 + 256 * j); *(f32x4*)(xr + lane * 4 + 256 * j) = v * rstd * w[j]; }
;     }
.Linvw_0:
	s_mov_b64 s[0:1], exec
	v_readlane_b32 s2, v253, 2
	v_readlane_b32 s3, v253, 3
	s_and_b64 s[2:3], s[0:1], s[2:3]
	s_mov_b64 exec, s[2:3]
	s_cbranch_execz .LBB0_637
	s_cmpk_lg_i32 s33, 0x100
	s_cbranch_scc1 .Lps_c_orig
	v_mov_b32_e32 v4, 0x1b71ac0
	v_mov_b32_e32 v5, 1
	global_atomic_add v4, v5, s[82:83]
	v_readfirstlane_b32 s97, v130
	s_cmpk_lt_u32 s97, 0x80
	s_cbranch_scc0 .LBB0_637
.Lps_c_poll:
	global_load_dword v6, v4, s[82:83] sc1
	s_waitcnt vmcnt(0)
	v_readfirstlane_b32 s97, v6
	s_cmpk_lt_u32 s97, 0x100
	s_cbranch_scc0 .LBB0_637
	s_sleep 1
	s_branch .Lps_c_poll
.Lps_c_orig:
	s_mov_b64 s[4:5], exec
	s_nop 0
	s_waitcnt vmcnt(0)
	s_waitcnt vmcnt(0)
	s_lshl_b32 s2, s89, 8
	v_readlane_b32 s6, v253, 0
	v_mbcnt_lo_u32_b32 v0, s4, 0
	v_readlane_b32 s7, v253, 1
	s_add_u32 s2, s6, s2
	v_mbcnt_hi_u32_b32 v0, s5, v0
	s_addc_u32 s3, s7, 0
	v_cmp_eq_u32_e32 vcc, 0, v0
	s_and_saveexec_b64 s[6:7], vcc
	s_cbranch_execz .LBB0_621
	s_bcnt1_i32_b64 s4, s[4:5]
	v_mov_b32_e32 v1, 0x1000
	v_mov_b32_e32 v2, s4
	global_atomic_add v1, v1, v2, s[2:3] sc0
